# attention unit epilogue: O/l staged through per-wave f32 LDS tile so gate loads and bf16 stores are row-contiguous 16-byte accesses
# speedup vs baseline: 1.0338x; 1.0309x over previous
.LBB0_630:
	v_readlane_b32 s4, v253, 38
	v_readlane_b32 s5, v253, 39
	v_readfirstlane_b32 s10, v134
	v_readfirstlane_b32 s11, v135
	v_mbcnt_lo_u32_b32 v0, -1, 0
	v_mbcnt_hi_u32_b32 v0, -1, v0
	s_lshl_b64 s[10:11], s[10:11], 1
	s_add_u32 s12, s4, s10
	s_addc_u32 s13, s5, s11
	s_add_u32 s14, s70, s10
	s_addc_u32 s15, s71, s11
	v_lshrrev_b32_e32 v1, 3, v0
	v_and_b32_e32 v5, 7, v0
	v_lshlrev_b32_e32 v6, 4, v5
	v_lshl_add_u32 v6, v1, 11, v6
	v_add_u32_e32 v7, 0x4000, v6
	v_add_u32_e32 v8, 0x8000, v6
	v_add_u32_e32 v9, 0xc000, v6
	global_load_dwordx4 v[46:49], v6, s[12:13]
	global_load_dwordx4 v[50:53], v7, s[12:13]
	global_load_dwordx4 v[54:57], v8, s[12:13]
	global_load_dwordx4 v[58:61], v9, s[12:13]
	s_cmp_lg_u32 s33, 0
	s_cbranch_scc1 .Lq_pf1
	s_mov_b64 s[10:11], exec
	s_mov_b64 exec, 1
	v_mov_b32_e32 v176, 1
	global_atomic_add v176, v13, v176, s[8:9] sc0
	s_mov_b64 exec, s[10:11]
.Lq_pf1:
	s_mul_i32 s16, s33, 0x2200
	s_add_i32 s16, s16, 0xf000
	v_and_b32_e32 v4, 31, v0
	v_mul_u32_u24_e32 v4, 0x110, v4
	v_lshrrev_b32_e32 v10, 5, v0
	v_lshl_add_u32 v4, v10, 4, v4
	v_add_u32_e32 v4, s16, v4
	v_mul_u32_u24_e32 v10, 0x110, v1
	v_lshlrev_b32_e32 v5, 5, v5
	v_add3_u32 v5, v10, v5, s16
	v_pk_mul_f32 v[14:15], v[14:15], v[2:3] op_sel_hi:[1,0]
	v_pk_mul_f32 v[16:17], v[16:17], v[2:3] op_sel_hi:[1,0]
	v_pk_mul_f32 v[18:19], v[18:19], v[2:3] op_sel_hi:[1,0]
	v_pk_mul_f32 v[20:21], v[20:21], v[2:3] op_sel_hi:[1,0]
	v_pk_mul_f32 v[22:23], v[22:23], v[2:3] op_sel_hi:[1,0]
	v_pk_mul_f32 v[24:25], v[24:25], v[2:3] op_sel_hi:[1,0]
	v_pk_mul_f32 v[26:27], v[26:27], v[2:3] op_sel_hi:[1,0]
	v_pk_mul_f32 v[28:29], v[28:29], v[2:3] op_sel_hi:[1,0]
	v_pk_mul_f32 v[30:31], v[30:31], v[2:3] op_sel_hi:[1,0]
	v_pk_mul_f32 v[32:33], v[32:33], v[2:3] op_sel_hi:[1,0]
	v_pk_mul_f32 v[34:35], v[34:35], v[2:3] op_sel_hi:[1,0]
	v_pk_mul_f32 v[36:37], v[36:37], v[2:3] op_sel_hi:[1,0]
	v_pk_mul_f32 v[38:39], v[38:39], v[2:3] op_sel_hi:[1,0]
	v_pk_mul_f32 v[40:41], v[40:41], v[2:3] op_sel_hi:[1,0]
	v_pk_mul_f32 v[42:43], v[42:43], v[2:3] op_sel_hi:[1,0]
	v_pk_mul_f32 v[44:45], v[44:45], v[2:3] op_sel_hi:[1,0]
	ds_write_b128 v4, v[14:17]
	ds_write_b128 v4, v[18:21] offset:32
	ds_write_b128 v4, v[22:25] offset:64
	ds_write_b128 v4, v[26:29] offset:96
	ds_write_b128 v4, v[30:33] offset:128
	ds_write_b128 v4, v[34:37] offset:160
	ds_write_b128 v4, v[38:41] offset:192
	ds_write_b128 v4, v[42:45] offset:224
	ds_read_b128 v[62:65], v5
	ds_read_b128 v[66:69], v5 offset:16
	ds_read_b128 v[70:73], v5 offset:2176
	ds_read_b128 v[74:77], v5 offset:2192
	ds_read_b128 v[78:81], v5 offset:4352
	ds_read_b128 v[82:85], v5 offset:4368
	ds_read_b128 v[86:89], v5 offset:6528
	ds_read_b128 v[90:93], v5 offset:6544
	s_waitcnt vmcnt(3)
	v_lshlrev_b32_e32 v94, 16, v46
	v_and_b32_e32 v95, 0xffff0000, v46
	v_lshlrev_b32_e32 v96, 16, v47
	v_and_b32_e32 v97, 0xffff0000, v47
	v_lshlrev_b32_e32 v98, 16, v48
	v_and_b32_e32 v99, 0xffff0000, v48
	v_lshlrev_b32_e32 v100, 16, v49
	v_and_b32_e32 v101, 0xffff0000, v49
	s_waitcnt lgkmcnt(6)
	v_pk_mul_f32 v[94:95], v[62:63], v[94:95]
	v_pk_mul_f32 v[96:97], v[64:65], v[96:97]
	v_pk_mul_f32 v[98:99], v[66:67], v[98:99]
	v_pk_mul_f32 v[100:101], v[68:69], v[100:101]
	v_cvt_pk_bf16_f32 v102, v94, v95
	v_cvt_pk_bf16_f32 v103, v96, v97
	v_cvt_pk_bf16_f32 v104, v98, v99
	v_cvt_pk_bf16_f32 v105, v100, v101
	global_store_dwordx4 v6, v[102:105], s[14:15]
	s_waitcnt vmcnt(3)
	v_lshlrev_b32_e32 v94, 16, v50
	v_and_b32_e32 v95, 0xffff0000, v50
	v_lshlrev_b32_e32 v96, 16, v51
	v_and_b32_e32 v97, 0xffff0000, v51
	v_lshlrev_b32_e32 v98, 16, v52
	v_and_b32_e32 v99, 0xffff0000, v52
	v_lshlrev_b32_e32 v100, 16, v53
	v_and_b32_e32 v101, 0xffff0000, v53
	s_waitcnt lgkmcnt(4)
	v_pk_mul_f32 v[94:95], v[70:71], v[94:95]
	v_pk_mul_f32 v[96:97], v[72:73], v[96:97]
	v_pk_mul_f32 v[98:99], v[74:75], v[98:99]
	v_pk_mul_f32 v[100:101], v[76:77], v[100:101]
	v_cvt_pk_bf16_f32 v106, v94, v95
	v_cvt_pk_bf16_f32 v107, v96, v97
	v_cvt_pk_bf16_f32 v108, v98, v99
	v_cvt_pk_bf16_f32 v109, v100, v101
	global_store_dwordx4 v7, v[106:109], s[14:15]
	s_waitcnt vmcnt(3)
	v_lshlrev_b32_e32 v94, 16, v54
	v_and_b32_e32 v95, 0xffff0000, v54
	v_lshlrev_b32_e32 v96, 16, v55
	v_and_b32_e32 v97, 0xffff0000, v55
	v_lshlrev_b32_e32 v98, 16, v56
	v_and_b32_e32 v99, 0xffff0000, v56
	v_lshlrev_b32_e32 v100, 16, v57
	v_and_b32_e32 v101, 0xffff0000, v57
	s_waitcnt lgkmcnt(2)
	v_pk_mul_f32 v[94:95], v[78:79], v[94:95]
	v_pk_mul_f32 v[96:97], v[80:81], v[96:97]
	v_pk_mul_f32 v[98:99], v[82:83], v[98:99]
	v_pk_mul_f32 v[100:101], v[84:85], v[100:101]
	v_cvt_pk_bf16_f32 v190, v94, v95
	v_cvt_pk_bf16_f32 v191, v96, v97
	v_cvt_pk_bf16_f32 v192, v98, v99
	v_cvt_pk_bf16_f32 v193, v100, v101
	global_store_dwordx4 v8, v[190:193], s[14:15]
	s_waitcnt vmcnt(3)
	v_lshlrev_b32_e32 v94, 16, v58
	v_and_b32_e32 v95, 0xffff0000, v58
	v_lshlrev_b32_e32 v96, 16, v59
	v_and_b32_e32 v97, 0xffff0000, v59
	v_lshlrev_b32_e32 v98, 16, v60
	v_and_b32_e32 v99, 0xffff0000, v60
	v_lshlrev_b32_e32 v100, 16, v61
	v_and_b32_e32 v101, 0xffff0000, v61
	s_waitcnt lgkmcnt(0)
	v_pk_mul_f32 v[94:95], v[86:87], v[94:95]
	v_pk_mul_f32 v[96:97], v[88:89], v[96:97]
	v_pk_mul_f32 v[98:99], v[90:91], v[98:99]
	v_pk_mul_f32 v[100:101], v[92:93], v[100:101]
	v_cvt_pk_bf16_f32 v194, v94, v95
	v_cvt_pk_bf16_f32 v195, v96, v97
	v_cvt_pk_bf16_f32 v196, v98, v99
	v_cvt_pk_bf16_f32 v197, v100, v101
	global_store_dwordx4 v9, v[194:197], s[14:15]
	s_mov_b64 s[4:5], 0
